# v037 + hyena halo-load pairing + phase E trailing LDS reads batched + raised priority for the dedicated latent-S5 blocks in phase D
# baseline (speedup 1.0000x reference)
.LBB0_1891:
	s_and_b64 vcc, exec, s[2:3]
	s_cbranch_vccz .LBB0_1949
	s_setprio 2
	v_mov_b32_e32 v3, v196
	s_lshl_b32 s0, s26, 1
	v_ashrrev_i32_e32 v67, 6, v3
	s_and_b32 s0, s0, 30
	v_ashrrev_i32_e32 v2, 7, v3
	v_and_b32_e32 v114, 1, v67
	v_add_u32_e32 v2, s0, v2
	v_lshlrev_b32_e32 v8, 5, v114
	v_readlane_b32 s0, v255, 17
	s_mov_b64 s[8:9], s[62:63]
	s_mov_b64 s[6:7], s[62:63]
	v_add3_u32 v40, v2, s0, v8
	s_mov_b64 s[0:1], s[62:63]
	v_ashrrev_i32_e32 v41, 31, v40
	v_lshlrev_b64 v[8:9], 12, v[40:41]
	v_and_b32_e32 v66, 63, v3
	v_lshl_add_u64 v[8:9], s[0:1], 0, v[8:9]
	s_mov_b64 s[0:1], s[62:63]
	s_mov_b64 s[2:3], s[62:63]
	v_lshlrev_b64 v[10:11], 9, v[40:41]
	v_lshlrev_b32_e32 v12, 3, v66
	v_lshl_add_u64 v[10:11], s[2:3], 0, v[10:11]
	v_mov_b32_e32 v13, v1
	v_lshl_add_u64 v[10:11], v[10:11], 0, v[12:13]
	v_add_co_u32_e32 v10, vcc, 0xe2c4000, v10
	v_and_b32_e32 v0, 15, v3
	s_nop 0
	v_addc_co_u32_e32 v11, vcc, 0, v11, vcc
	global_load_dwordx2 v[92:93], v[10:11], off
	s_waitcnt vmcnt(1)
	v_and_b32_e32 v56, 48, v3
	v_mov_b32_e32 v57, v1
	v_lshlrev_b32_e32 v10, 4, v0
	v_lshl_add_u64 v[8:9], v[8:9], 0, v[56:57]
	s_mov_b64 s[2:3], 0xe2d4000
	v_cmp_gt_u32_e32 vcc, 32, v66
	v_lshl_add_u64 v[42:43], v[8:9], 0, s[2:3]
	v_mov_b32_e32 v8, 0
	v_lshlrev_b32_e32 v44, 1, v10
	v_mov_b32_e32 v12, 0
	v_mov_b32_e32 v13, 0
	v_mov_b32_e32 v14, 0
	v_mov_b32_e32 v15, 0
	s_and_saveexec_b64 s[2:3], vcc
	s_cbranch_execz .LBB0_1894
	v_mov_b32_e32 v45, v1
	v_lshl_add_u64 v[10:11], v[42:43], 0, v[44:45]
	global_load_dwordx4 v[12:15], v[10:11], off

.LBB0_1947:
	s_setprio 0
	s_mov_b64 s[0:1], s[62:63]
	v_readlane_b32 s2, v255, 12
	v_readlane_b32 s3, v255, 13
	s_nop 3
	s_lshl_b64 s[2:3], s[2:3], 2
	s_add_u32 s0, s0, s2
	s_addc_u32 s1, s1, s3
	s_add_u32 s6, s0, 0xe2c3840
	s_addc_u32 s7, s1, 0
	s_branch .LBB0_1585
	s_and_b64 vcc, exec, s[0:1]
	s_cbranch_vccz .LBB0_1949
	s_ashr_i32 s3, s2, 31
	s_lshl_b64 s[2:3], s[2:3], 2
	v_or_b32_e32 v0, s2, v114
	v_mov_b32_e32 v9, s3
	v_readlane_b32 s2, v255, 18
	s_mov_b64 s[0:1], s[60:61]
	v_lshlrev_b64 v[2:3], 9, v[2:3]
	v_or_b32_e32 v8, s2, v0
	v_lshlrev_b64 v[8:9], 14, v[8:9]
	v_lshl_add_u64 v[8:9], s[0:1], 0, v[8:9]
	v_lshl_add_u64 v[2:3], v[8:9], 0, v[2:3]
	v_mov_b32_e32 v95, v1
	v_lshl_add_u64 v[2:3], v[2:3], 0, v[94:95]
	v_add_co_u32_e32 v2, vcc, 0x3000000, v2
	v_readlane_b32 s3, v255, 19
	s_nop 0
	v_addc_co_u32_e32 v3, vcc, 0, v3, vcc
	global_store_dwordx2 v[2:3], v[112:113], off
